# epilogue-length start stagger (3x s_sleep 127, ~10us) for WGs >= 256 at the start of GEMM phases 1,5,10,14, on top of v_p11dyn
# speedup vs baseline: 1.0017x; 1.0014x over previous
.LBB0_203:
	s_or_b64 exec, exec, s[0:1]
	s_cmpk_lt_i32 s2, 0x1000
	s_cselect_b64 s[18:19], -1, 0
	s_cmpk_gt_i32 s2, 0xfff
	s_waitcnt lgkmcnt(0)
	s_barrier
	s_cbranch_scc1 .LBB0_276
	s_add_u32 s3, s72, 0x3000000
	s_addc_u32 s34, s73, 0
	s_add_u32 s8, s72, 0x7000000
	s_addc_u32 s9, s73, 0
	s_add_u32 s12, s72, 0x13200000
	s_addc_u32 s13, s73, 0
	s_add_u32 s14, s72, 0x7200000
	s_addc_u32 s15, s73, 0
	s_add_u32 s16, s72, 0xb200000
	s_addc_u32 s17, s73, 0
	s_add_u32 s20, s72, 0xf200000
	s_addc_u32 s21, s73, 0
	v_mov_b32_e32 v153, 0
	s_mov_b64 s[22:23], 0x20000
	s_mov_b32 s35, 0x20000
	s_mov_b64 s[24:25], 0x40000
	s_mov_b32 s36, 0x40000
	s_mov_b64 s[28:29], 0x60000
	s_mov_b32 s37, 0x60000
	s_mov_b32 s31, 0
	s_movk_i32 s38, 0x7f
	s_movk_i32 s39, 0x4c
	s_movk_i32 s40, 0x5c
	s_movk_i32 s41, 0x6c
	s_movk_i32 s42, 0x7c
	s_mov_b32 s43, 0xc2fc0000
	s_mov_b32 s44, 0x3f2aaaab
	s_mov_b32 s45, 0x3f317218
	s_mov_b32 s46, 0x33800000
	s_movk_i32 s47, 0x7fff
	s_movk_i32 s48, 0x7e
	s_movk_i32 s49, 0x7d
	s_movk_i32 s50, 0x7f00
	s_movk_i32 s51, 0x3f9c
	s_movk_i32 s56, 0x3fac
	s_movk_i32 s57, 0x3fbc
	s_movk_i32 s58, 0x3fcc
	s_movk_i32 s59, 0x3fdc
	s_movk_i32 s62, 0x3fec
	s_movk_i32 s63, 0x3ffc
	v_mov_b32_e32 v166, 0x50
	v_mov_b32_e32 v167, 0x60
	v_mov_b32_e32 v168, 0x70
	v_mov_b32_e32 v169, 0x42800000
	v_not_b32_e32 v170, 63
	v_mov_b32_e32 v171, 0x4c
	v_mov_b32_e32 v172, 0x5c
	v_mov_b32_e32 v173, 0x6c
	v_mov_b32_e32 v174, 0x7c
	s_mov_b32 s64, s2
	s_cmpk_lt_u32 s2, 0x100
	s_cbranch_scc1 .Lmid_stag_0
	s_sleep 127
	s_sleep 127
	s_sleep 127
.Lmid_stag_0:
	s_branch .LBB0_207

.LBB0_500:
	s_or_b64 exec, exec, s[0:1]
	s_cmpk_lt_i32 s2, 0x800
	s_cselect_b64 s[0:1], -1, 0
	s_cmpk_gt_i32 s2, 0x7ff
	s_waitcnt lgkmcnt(0)
	s_barrier
	s_cbranch_scc1 .LBB0_505
	s_add_u32 s3, s72, 0x3000000
	s_addc_u32 s4, s73, 0
	s_add_u32 s6, s72, 0x7000000
	s_addc_u32 s7, s73, 0
	s_add_u32 s8, s72, 0x7200000
	s_addc_u32 s9, s73, 0
	s_add_u32 s5, s72, 0x7100000
	s_addc_u32 s26, s73, 0
	s_mov_b32 s15, 0
	s_waitcnt vmcnt(9)
	v_mov_b32_e32 v153, 0
	s_mov_b64 s[16:17], 0x20000
	s_mov_b32 s27, 0x20000
	s_mov_b64 s[22:23], 0x40000
	s_mov_b32 s30, 0x40000
	s_mov_b64 s[24:25], 0x60000
	s_mov_b32 s31, 0x60000
	v_mov_b32_e32 v194, 0x4000
	s_mov_b32 s34, s2
	s_cmpk_lt_u32 s2, 0x100
	s_cbranch_scc1 .Lmid_stag_2
	s_sleep 127
	s_sleep 127
	s_sleep 127
.Lmid_stag_2:
.LBB0_502:
	s_ashr_i32 s14, s34, 3
	s_lshr_b32 s28, s14, 28
	s_add_i32 s28, s14, s28
	s_and_b32 s29, s28, -16
	s_sub_i32 s33, s14, s29
	s_lshl_b32 s14, s28, 7
	s_lshl_b32 s28, s34, 8
	s_and_b32 s14, s14, 0xfffff800
	s_and_b32 s28, s28, 0x700
	s_or_b32 s28, s14, s28
	s_ashr_i32 s29, s28, 31
	s_lshl_b32 s35, s33, 7
	s_lshl_b64 s[36:37], s[28:29], 11
	s_add_u32 s36, s3, s36
	s_addc_u32 s37, s4, s37
	s_add_i32 s14, s35, 0x1000
	v_mov_b32_e32 v36, v220
	s_lshl_b64 s[38:39], s[14:15], 11
	s_add_u32 s38, s72, s38
	v_ashrrev_i32_e32 v26, 2, v36
	v_ashrrev_i32_e32 v27, 31, v26
	s_addc_u32 s39, s73, s39
	v_lshlrev_b64 v[0:1], 11, v[26:27]
	v_lshlrev_b32_e32 v4, 4, v36
	v_lshl_add_u64 v[2:3], s[38:39], 0, v[0:1]
	v_lshl_add_u64 v[0:1], s[36:37], 0, v[0:1]
	v_and_b32_e32 v152, 48, v4
	v_lshl_add_u64 v[154:155], v[0:1], 0, v[152:153]
	v_add_co_u32_e32 v28, vcc, s27, v154
	v_lshl_add_u64 v[156:157], v[2:3], 0, v[152:153]
	s_nop 0
	v_addc_co_u32_e32 v29, vcc, 0, v155, vcc
	v_add_co_u32_e32 v30, vcc, s30, v154
	global_load_dwordx4 v[2:5], v[154:155], off
	s_nop 0
	v_addc_co_u32_e32 v31, vcc, 0, v155, vcc
	v_add_co_u32_e32 v32, vcc, s31, v154
	global_load_dwordx4 v[6:9], v[28:29], off
	s_nop 0
	v_addc_co_u32_e32 v33, vcc, 0, v155, vcc
	v_add_co_u32_e32 v34, vcc, s27, v156
	global_load_dwordx4 v[10:13], v[30:31], off
	s_nop 0
	v_addc_co_u32_e32 v35, vcc, 0, v157, vcc
	global_load_dwordx4 v[14:17], v[32:33], off
	global_load_dwordx4 v[18:21], v[156:157], off
	global_load_dwordx4 v[22:25], v[34:35], off
	global_load_dwordx4 v[44:47], v[154:155], off offset:64
	global_load_dwordx4 v[60:63], v[28:29], off offset:64
	global_load_dwordx4 v[68:71], v[30:31], off offset:64
	global_load_dwordx4 v[140:143], v[32:33], off offset:64
	global_load_dwordx4 v[52:55], v[156:157], off offset:64
	global_load_dwordx4 v[144:147], v[34:35], off offset:64
	v_lshrrev_b32_e32 v27, 4, v36
	v_lshrrev_b32_e32 v37, 2, v36
	v_sub_u32_e32 v40, 0, v27
	v_sub_u32_e32 v37, 0, v37
	v_and_b32_e32 v38, 0x3ffff8f, v36
	v_lshlrev_b32_e32 v39, 6, v36
	v_xor_b32_e32 v36, v36, v40
	v_xor_b32_e32 v27, v27, v37
	v_lshlrev_b32_e32 v36, 4, v36
	v_lshlrev_b32_e32 v27, 4, v27
	v_and_b32_e32 v41, 0x1000, v39
	v_and_b32_e32 v36, 48, v36
	v_and_b32_e32 v27, 48, v27
	v_and_b32_e32 v42, 0x3c0, v39
	v_and_b32_e32 v39, 0xffffe3c0, v39
	v_lshl_add_u32 v38, v38, 6, v194
	v_lshl_or_b32 v152, v26, 6, v36
	v_or_b32_e32 v26, v27, v41
	s_mov_b32 s29, -2
	s_mov_b32 s36, s15
	v_mov_b32_e32 v0, 0
	v_mov_b32_e32 v1, v153
	v_or3_b32 v166, v41, v42, v27
	v_add_u32_e32 v167, v27, v39
	v_add_u32_e32 v168, v27, v38
	v_add_u32_e32 v169, v26, v42
	v_lshl_add_u64 v[158:159], v[154:155], 0, s[16:17]
	v_lshl_add_u64 v[160:161], v[154:155], 0, s[22:23]
	v_lshl_add_u64 v[162:163], v[154:155], 0, s[24:25]
	v_lshl_add_u64 v[164:165], v[156:157], 0, s[16:17]
	v_mov_b32_e32 v26, v153
	v_mov_b32_e32 v27, v153
	v_mov_b32_e32 v28, 0
	v_mov_b32_e32 v29, v153
	v_mov_b32_e32 v30, v153
	v_mov_b32_e32 v31, v153
	v_mov_b32_e32 v32, 0
	v_mov_b32_e32 v33, v153
	v_mov_b32_e32 v34, v153
	v_mov_b32_e32 v35, v153
	v_mov_b32_e32 v36, 0
	v_mov_b32_e32 v37, v153
	v_mov_b32_e32 v38, v153
	v_mov_b32_e32 v39, v153
	v_mov_b32_e32 v40, 0
	v_mov_b32_e32 v41, v153
	v_mov_b32_e32 v42, v153
	v_mov_b32_e32 v43, v153
	v_mov_b32_e32 v48, 0
	s_waitcnt vmcnt(11)
	ds_write_b128 v152, v[2:5]
	s_waitcnt vmcnt(10)
	ds_write_b128 v152, v[6:9] offset:4096
	s_waitcnt vmcnt(9)
	ds_write_b128 v152, v[10:13] offset:8192
	s_waitcnt vmcnt(8)
	ds_write_b128 v152, v[14:17] offset:12288
	s_waitcnt vmcnt(7)
	ds_write_b128 v152, v[18:21] offset:32768
	s_waitcnt vmcnt(6)
	ds_write_b128 v152, v[22:25] offset:36864
	v_mov_b32_e32 v2, v153
	v_mov_b32_e32 v3, v153
	v_mov_b32_e32 v4, 0
	v_mov_b32_e32 v5, v153
	v_mov_b32_e32 v6, v153
	v_mov_b32_e32 v7, v153
	v_mov_b32_e32 v8, 0
	v_mov_b32_e32 v9, v153
	v_mov_b32_e32 v10, v153
	v_mov_b32_e32 v11, v153
	v_mov_b32_e32 v12, 0
	v_mov_b32_e32 v13, v153
	v_mov_b32_e32 v14, v153
	v_mov_b32_e32 v15, v153
	v_mov_b32_e32 v16, 0
	v_mov_b32_e32 v17, v153
	v_mov_b32_e32 v18, v153
	v_mov_b32_e32 v19, v153
	v_mov_b32_e32 v20, 0
	v_mov_b32_e32 v21, v153
	v_mov_b32_e32 v22, v153
	v_mov_b32_e32 v23, v153
	v_mov_b32_e32 v24, 0
	v_mov_b32_e32 v25, v153
	v_mov_b32_e32 v49, v153
	v_mov_b32_e32 v50, v153
	v_mov_b32_e32 v51, v153
	v_mov_b32_e32 v56, 0
	v_mov_b32_e32 v57, v153
	v_mov_b32_e32 v58, v153
	v_mov_b32_e32 v59, v153
	v_mov_b32_e32 v64, 0
	v_mov_b32_e32 v65, v153
	v_mov_b32_e32 v66, v153
	v_mov_b32_e32 v67, v153
	v_mov_b32_e32 v72, 0
	v_mov_b32_e32 v73, v153
	v_mov_b32_e32 v74, v153
	v_mov_b32_e32 v75, v153
	v_mov_b32_e32 v76, 0
	v_mov_b32_e32 v77, v153
	v_mov_b32_e32 v78, v153
	v_mov_b32_e32 v79, v153
	v_mov_b32_e32 v80, 0
	v_mov_b32_e32 v81, v153
	v_mov_b32_e32 v82, v153
	v_mov_b32_e32 v83, v153
	v_mov_b32_e32 v84, 0
	v_mov_b32_e32 v85, v153
	v_mov_b32_e32 v86, v153
	v_mov_b32_e32 v87, v153
	v_mov_b32_e32 v88, 0
	v_mov_b32_e32 v89, v153
	v_mov_b32_e32 v90, v153
	v_mov_b32_e32 v91, v153
	v_mov_b32_e32 v92, 0
	v_mov_b32_e32 v93, v153
	v_mov_b32_e32 v94, v153
	v_mov_b32_e32 v95, v153
	v_mov_b32_e32 v96, 0
	v_mov_b32_e32 v97, v153
	v_mov_b32_e32 v98, v153
	v_mov_b32_e32 v99, v153
	v_mov_b32_e32 v100, 0
	v_mov_b32_e32 v101, v153
	v_mov_b32_e32 v102, v153
	v_mov_b32_e32 v103, v153
	v_mov_b32_e32 v104, 0
	v_mov_b32_e32 v105, v153
	v_mov_b32_e32 v106, v153
	v_mov_b32_e32 v107, v153
	v_mov_b32_e32 v108, 0
	v_mov_b32_e32 v109, v153
	v_mov_b32_e32 v110, v153
	v_mov_b32_e32 v111, v153
	v_mov_b32_e32 v112, 0
	v_mov_b32_e32 v113, v153
	v_mov_b32_e32 v114, v153
	v_mov_b32_e32 v115, v153
	v_mov_b32_e32 v116, 0
	v_mov_b32_e32 v117, v153
	v_mov_b32_e32 v118, v153
	v_mov_b32_e32 v119, v153
	v_mov_b32_e32 v120, 0
	v_mov_b32_e32 v121, v153
	v_mov_b32_e32 v122, v153
	v_mov_b32_e32 v123, v153
	v_mov_b32_e32 v124, 0
	v_mov_b32_e32 v125, v153
	v_mov_b32_e32 v126, v153
	v_mov_b32_e32 v127, v153
	v_mov_b32_e32 v128, 0
	v_mov_b32_e32 v129, v153
	v_mov_b32_e32 v130, v153
	v_mov_b32_e32 v131, v153
	v_mov_b32_e32 v132, 0
	v_mov_b32_e32 v133, v153
	v_mov_b32_e32 v134, v153
	v_mov_b32_e32 v135, v153
	v_mov_b32_e32 v136, 0
	v_mov_b32_e32 v137, v153
	v_mov_b32_e32 v138, v153
	v_mov_b32_e32 v139, v153
	v_mov_b32_e32 v148, 0
	v_mov_b32_e32 v149, v153
	v_mov_b32_e32 v150, v153
	v_mov_b32_e32 v151, v153
	s_waitcnt lgkmcnt(0)
	s_add_i32 s37, s36, 64
	s_min_u32 s14, s37, 0x3e0
	s_lshl_b32 s14, s14, 1
	v_lshl_add_u64 v[170:171], v[154:155], 0, s[14:15]
	v_lshl_add_u64 v[174:175], v[158:159], 0, s[14:15]
	v_lshl_add_u64 v[178:179], v[160:161], 0, s[14:15]
	v_lshl_add_u64 v[182:183], v[162:163], 0, s[14:15]
	v_lshl_add_u64 v[186:187], v[156:157], 0, s[14:15]
	v_lshl_add_u64 v[190:191], v[164:165], 0, s[14:15]

.LBB0_697:
	s_or_b64 exec, exec, s[0:1]
	s_cmpk_gt_i32 s2, 0xbff
	s_waitcnt lgkmcnt(0)
	s_barrier
	s_cbranch_scc1 .LBB0_712
	s_add_u32 s14, s72, 0x7040000
	s_addc_u32 s15, s73, 0
	s_add_u32 s3, s72, 0x7200000
	s_addc_u32 s4, s73, 0
	s_add_u32 s5, s72, 0x1b200000
	s_addc_u32 s6, s73, 0
	s_add_u32 s7, s72, 0x1000000
	s_addc_u32 s8, s73, 0
	s_mov_b32 s17, 0
	s_waitcnt vmcnt(9)
	v_mov_b32_e32 v153, 0
	s_mov_b64 s[22:23], 0x20000
	s_mov_b32 s9, 0x20000
	s_mov_b64 s[24:25], 0x40000
	s_mov_b32 s31, 0x40000
	s_mov_b64 s[28:29], 0x60000
	s_mov_b32 s35, 0x60000
	v_mov_b32_e32 v166, 0x358637bd
	s_mov_b32 s30, 0x3a800000
	s_mov_b32 s40, 0x800000
	s_movk_i32 s41, 0x3f8f
	s_movk_i32 s42, 0x3f9f
	s_movk_i32 s43, 0x3faf
	s_movk_i32 s44, 0x3fbf
	s_movk_i32 s45, 0x3fcf
	s_movk_i32 s46, 0x3fdf
	s_movk_i32 s47, 0x3fef
	s_movk_i32 s48, 0x3fff
	s_mov_b32 s34, 0x358637bd
	s_movk_i32 s49, 0xfe
	s_mov_b64 s[36:37], 0x60
	s_movk_i32 s50, 0xff
	v_mov_b32_e32 v167, 0x4000
	s_mov_b32 s51, s2
	s_cmpk_lt_u32 s2, 0x100
	s_cbranch_scc1 .Lmid_stag_1
	s_sleep 127
	s_sleep 127
	s_sleep 127
.Lmid_stag_1:
	s_branch .LBB0_700

.LBB0_1734:
	s_or_b64 exec, exec, s[0:1]
	v_readlane_b32 s0, v254, 30
	v_readlane_b32 s1, v254, 31
	s_and_b64 vcc, exec, s[0:1]
	s_waitcnt lgkmcnt(0)
	s_barrier
	s_cbranch_vccnz .LBB0_1739
	s_add_u32 s3, s72, 0x1b200000
	s_addc_u32 s4, s73, 0
	s_add_u32 s5, s72, 0x1a20000
	s_addc_u32 s6, s73, 0
	s_add_u32 s0, s72, 0x7040000
	s_addc_u32 s1, s73, 0
	s_add_u32 s10, s72, 0x13200000
	s_addc_u32 s11, s73, 0
	s_mov_b32 s13, 0
	s_waitcnt vmcnt(9)
	v_mov_b32_e32 v153, 0
	s_mov_b64 s[14:15], 0x20000
	s_mov_b32 s7, 0x20000
	s_mov_b64 s[16:17], 0x40000
	s_mov_b32 s8, 0x40000
	s_mov_b64 s[18:19], 0x60000
	s_mov_b32 s9, 0x60000
	v_mov_b32_e32 v166, 0x4000
	v_mov_b32_e32 v167, 0x358637bd
	s_mov_b32 s22, 0x800000
	s_mov_b32 s23, s2
	s_cmpk_lt_u32 s2, 0x100
	s_cbranch_scc1 .Lmid_stag_3
	s_sleep 127
	s_sleep 127
	s_sleep 127
.Lmid_stag_3:
.LBB0_1736:
	s_ashr_i32 s12, s23, 3
	s_lshr_b32 s20, s12, 28
	s_add_i32 s20, s12, s20
	s_and_b32 s21, s20, 0x1fffff0
	s_sub_i32 s12, s12, s21
	s_lshl_b32 s20, s20, 7
	s_lshl_b32 s21, s23, 8
	s_and_b32 s20, s20, 0xfffff800
	s_and_b32 s21, s21, 0x700
	s_or_b32 s20, s20, s21
	s_ashr_i32 s21, s20, 31
	s_lshl_b32 s24, s12, 7
	s_lshl_b64 s[26:27], s[20:21], 11
	s_add_u32 s26, s3, s26
	s_addc_u32 s27, s4, s27
	s_add_i32 s12, s24, 0x880
	v_mov_b32_e32 v36, v220
	s_lshl_b64 s[28:29], s[12:13], 11
	s_add_u32 s28, s5, s28
	v_ashrrev_i32_e32 v26, 2, v36
	v_ashrrev_i32_e32 v27, 31, v26
	s_addc_u32 s29, s6, s29
	v_lshlrev_b64 v[0:1], 11, v[26:27]
	v_lshlrev_b32_e32 v4, 4, v36
	v_lshl_add_u64 v[2:3], s[28:29], 0, v[0:1]
	v_lshl_add_u64 v[0:1], s[26:27], 0, v[0:1]
	v_and_b32_e32 v152, 48, v4
	v_lshl_add_u64 v[154:155], v[0:1], 0, v[152:153]
	v_add_co_u32_e32 v28, vcc, s7, v154
	v_lshl_add_u64 v[156:157], v[2:3], 0, v[152:153]
	s_nop 0
	v_addc_co_u32_e32 v29, vcc, 0, v155, vcc
	v_add_co_u32_e32 v30, vcc, s8, v154
	global_load_dwordx4 v[2:5], v[154:155], off
	s_nop 0
	v_addc_co_u32_e32 v31, vcc, 0, v155, vcc
	v_add_co_u32_e32 v32, vcc, s9, v154
	global_load_dwordx4 v[6:9], v[28:29], off
	s_nop 0
	v_addc_co_u32_e32 v33, vcc, 0, v155, vcc
	v_add_co_u32_e32 v34, vcc, s7, v156
	global_load_dwordx4 v[10:13], v[30:31], off
	s_nop 0
	v_addc_co_u32_e32 v35, vcc, 0, v157, vcc
	global_load_dwordx4 v[14:17], v[32:33], off
	global_load_dwordx4 v[18:21], v[156:157], off
	global_load_dwordx4 v[22:25], v[34:35], off
	global_load_dwordx4 v[120:123], v[154:155], off offset:64
	global_load_dwordx4 v[124:127], v[28:29], off offset:64
	global_load_dwordx4 v[128:131], v[30:31], off offset:64
	global_load_dwordx4 v[136:139], v[32:33], off offset:64
	global_load_dwordx4 v[132:135], v[156:157], off offset:64
	global_load_dwordx4 v[140:143], v[34:35], off offset:64
	v_lshrrev_b32_e32 v27, 4, v36
	v_lshrrev_b32_e32 v37, 2, v36
	v_sub_u32_e32 v40, 0, v27
	v_sub_u32_e32 v37, 0, v37
	v_and_b32_e32 v38, 0x3ffff8f, v36
	v_lshlrev_b32_e32 v39, 6, v36
	v_xor_b32_e32 v36, v36, v40
	v_xor_b32_e32 v27, v27, v37
	v_lshlrev_b32_e32 v36, 4, v36
	v_lshlrev_b32_e32 v27, 4, v27
	v_and_b32_e32 v41, 0x1000, v39
	v_and_b32_e32 v36, 48, v36
	v_and_b32_e32 v27, 48, v27
	v_and_b32_e32 v42, 0x3c0, v39
	v_and_b32_e32 v39, 0xffffe3c0, v39
	v_lshl_add_u32 v38, v38, 6, v166
	v_lshl_or_b32 v152, v26, 6, v36
	v_or_b32_e32 v26, v27, v41
	s_mov_b32 s21, -2
	s_mov_b32 s25, s13
	v_mov_b32_e32 v0, 0
	v_mov_b32_e32 v1, v153
	v_or3_b32 v168, v41, v42, v27
	v_add_u32_e32 v169, v27, v39
	v_add_u32_e32 v170, v27, v38
	v_add_u32_e32 v171, v26, v42
	v_lshl_add_u64 v[158:159], v[154:155], 0, s[14:15]
	v_lshl_add_u64 v[160:161], v[154:155], 0, s[16:17]
	v_lshl_add_u64 v[162:163], v[154:155], 0, s[18:19]
	v_lshl_add_u64 v[164:165], v[156:157], 0, s[14:15]
	v_mov_b32_e32 v26, v153
	v_mov_b32_e32 v27, v153
	v_mov_b32_e32 v28, 0
	v_mov_b32_e32 v29, v153
	v_mov_b32_e32 v30, v153
	v_mov_b32_e32 v31, v153
	v_mov_b32_e32 v32, 0
	v_mov_b32_e32 v33, v153
	v_mov_b32_e32 v34, v153
	v_mov_b32_e32 v35, v153
	v_mov_b32_e32 v36, 0
	v_mov_b32_e32 v37, v153
	v_mov_b32_e32 v38, v153
	v_mov_b32_e32 v39, v153
	v_mov_b32_e32 v40, 0
	v_mov_b32_e32 v41, v153
	v_mov_b32_e32 v42, v153
	v_mov_b32_e32 v43, v153
	v_mov_b32_e32 v44, 0
	s_waitcnt vmcnt(11)
	ds_write_b128 v152, v[2:5]
	s_waitcnt vmcnt(10)
	ds_write_b128 v152, v[6:9] offset:4096
	s_waitcnt vmcnt(9)
	ds_write_b128 v152, v[10:13] offset:8192
	s_waitcnt vmcnt(8)
	ds_write_b128 v152, v[14:17] offset:12288
	s_waitcnt vmcnt(7)
	ds_write_b128 v152, v[18:21] offset:32768
	s_waitcnt vmcnt(6)
	ds_write_b128 v152, v[22:25] offset:36864
	v_mov_b32_e32 v2, v153
	v_mov_b32_e32 v3, v153
	v_mov_b32_e32 v4, 0
	v_mov_b32_e32 v5, v153
	v_mov_b32_e32 v6, v153
	v_mov_b32_e32 v7, v153
	v_mov_b32_e32 v8, 0
	v_mov_b32_e32 v9, v153
	v_mov_b32_e32 v10, v153
	v_mov_b32_e32 v11, v153
	v_mov_b32_e32 v12, 0
	v_mov_b32_e32 v13, v153
	v_mov_b32_e32 v14, v153
	v_mov_b32_e32 v15, v153
	v_mov_b32_e32 v16, 0
	v_mov_b32_e32 v17, v153
	v_mov_b32_e32 v18, v153
	v_mov_b32_e32 v19, v153
	v_mov_b32_e32 v20, 0
	v_mov_b32_e32 v21, v153
	v_mov_b32_e32 v22, v153
	v_mov_b32_e32 v23, v153
	v_mov_b32_e32 v24, 0
	v_mov_b32_e32 v25, v153
	v_mov_b32_e32 v45, v153
	v_mov_b32_e32 v46, v153
	v_mov_b32_e32 v47, v153
	v_mov_b32_e32 v48, 0
	v_mov_b32_e32 v49, v153
	v_mov_b32_e32 v50, v153
	v_mov_b32_e32 v51, v153
	v_mov_b32_e32 v52, 0
	v_mov_b32_e32 v53, v153
	v_mov_b32_e32 v54, v153
	v_mov_b32_e32 v55, v153
	v_mov_b32_e32 v56, 0
	v_mov_b32_e32 v57, v153
	v_mov_b32_e32 v58, v153
	v_mov_b32_e32 v59, v153
	v_mov_b32_e32 v60, 0
	v_mov_b32_e32 v61, v153
	v_mov_b32_e32 v62, v153
	v_mov_b32_e32 v63, v153
	v_mov_b32_e32 v64, 0
	v_mov_b32_e32 v65, v153
	v_mov_b32_e32 v66, v153
	v_mov_b32_e32 v67, v153
	v_mov_b32_e32 v68, 0
	v_mov_b32_e32 v69, v153
	v_mov_b32_e32 v70, v153
	v_mov_b32_e32 v71, v153
	v_mov_b32_e32 v72, 0
	v_mov_b32_e32 v73, v153
	v_mov_b32_e32 v74, v153
	v_mov_b32_e32 v75, v153
	v_mov_b32_e32 v76, 0
	v_mov_b32_e32 v77, v153
	v_mov_b32_e32 v78, v153
	v_mov_b32_e32 v79, v153
	v_mov_b32_e32 v80, 0
	v_mov_b32_e32 v81, v153
	v_mov_b32_e32 v82, v153
	v_mov_b32_e32 v83, v153
	v_mov_b32_e32 v84, 0
	v_mov_b32_e32 v85, v153
	v_mov_b32_e32 v86, v153
	v_mov_b32_e32 v87, v153
	v_mov_b32_e32 v88, 0
	v_mov_b32_e32 v89, v153
	v_mov_b32_e32 v90, v153
	v_mov_b32_e32 v91, v153
	v_mov_b32_e32 v92, 0
	v_mov_b32_e32 v93, v153
	v_mov_b32_e32 v94, v153
	v_mov_b32_e32 v95, v153
	v_mov_b32_e32 v96, 0
	v_mov_b32_e32 v97, v153
	v_mov_b32_e32 v98, v153
	v_mov_b32_e32 v99, v153
	v_mov_b32_e32 v100, 0
	v_mov_b32_e32 v101, v153
	v_mov_b32_e32 v102, v153
	v_mov_b32_e32 v103, v153
	v_mov_b32_e32 v104, 0
	v_mov_b32_e32 v105, v153
	v_mov_b32_e32 v106, v153
	v_mov_b32_e32 v107, v153
	v_mov_b32_e32 v108, 0
	v_mov_b32_e32 v109, v153
	v_mov_b32_e32 v110, v153
	v_mov_b32_e32 v111, v153
	v_mov_b32_e32 v112, 0
	v_mov_b32_e32 v113, v153
	v_mov_b32_e32 v114, v153
	v_mov_b32_e32 v115, v153
	v_mov_b32_e32 v116, 0
	v_mov_b32_e32 v117, v153
	v_mov_b32_e32 v118, v153
	v_mov_b32_e32 v119, v153
	v_mov_b32_e32 v144, 0
	v_mov_b32_e32 v145, v153
	v_mov_b32_e32 v146, v153
	v_mov_b32_e32 v147, v153
	v_mov_b32_e32 v148, 0
	v_mov_b32_e32 v149, v153
	v_mov_b32_e32 v150, v153
	v_mov_b32_e32 v151, v153
	s_waitcnt lgkmcnt(0)
	s_add_i32 s26, s25, 64
	s_min_u32 s12, s26, 0x3e0
	s_lshl_b32 s12, s12, 1
	v_lshl_add_u64 v[172:173], v[154:155], 0, s[12:13]
	v_lshl_add_u64 v[176:177], v[158:159], 0, s[12:13]
	v_lshl_add_u64 v[180:181], v[160:161], 0, s[12:13]
	v_lshl_add_u64 v[184:185], v[162:163], 0, s[12:13]
	v_lshl_add_u64 v[188:189], v[156:157], 0, s[12:13]
	v_lshl_add_u64 v[192:193], v[164:165], 0, s[12:13]
